# K-loop heads aligned to 64 bytes
# speedup vs baseline: 1.0101x; 1.0101x over previous
.LBB0_119:
	s_ashr_i32 s81, s80, 31
	s_lshl_b64 s[52:53], s[80:81], 19
	s_add_u32 s82, s12, s52
	s_addc_u32 s83, s13, s53
	s_and_b64 s[52:53], s[6:7], exec
	s_cselect_b32 s52, s83, s89
	s_cselect_b32 s53, s82, s88
	s_ashr_i32 s79, s78, 31
	s_lshl_b64 s[56:57], s[78:79], 19
	s_add_u32 s84, s14, s56
	s_addc_u32 s85, s15, s57
	s_and_b64 s[56:57], s[6:7], exec
	s_cselect_b32 s56, s85, s91
	s_cselect_b32 s57, s84, s90
	s_add_u32 s88, s88, 0x40080
	s_addc_u32 s89, s89, 0
	s_add_u32 s58, s90, 0x100
	v_mov_b32_e32 v0, 0
	s_addc_u32 s59, s91, 0
	s_mov_b32 s66, -2
	s_waitcnt lgkmcnt(0)
	.p2align 6

.LBB0_271:
	s_add_u32 s86, s86, 0xb0080
	s_addc_u32 s87, s87, 0
	s_add_u32 s56, s88, 0x100
	v_mov_b32_e32 v0, 0
	s_addc_u32 s57, s89, 0
	s_mov_b32 s58, -2
	.p2align 6

.LBB0_428:
	s_ashr_i32 s95, s94, 31
	s_lshl_b64 s[16:17], s[94:95], 19
	s_add_u32 s96, s12, s16
	s_addc_u32 s97, s13, s17
	s_and_b64 s[16:17], s[8:9], exec
	s_cselect_b32 s15, s97, s89
	s_cselect_b32 s16, s96, s88
	s_ashr_i32 s85, s84, 31
	s_lshl_b64 s[18:19], s[84:85], 19
	s_add_u32 s90, s54, s18
	s_addc_u32 s91, s55, s19
	s_and_b64 s[18:19], s[8:9], exec
	s_cselect_b32 s17, s91, s7
	s_cselect_b32 s18, s90, s6
	s_add_u32 s88, s88, 0x40080
	s_addc_u32 s89, s89, 0
	s_add_u32 s19, s6, 0x100
	v_mov_b32_e32 v0, 0
	s_addc_u32 s20, s7, 0
	s_mov_b32 s21, -2
	s_waitcnt lgkmcnt(0)
	.p2align 6

.LBB0_992:
	s_ashr_i32 s53, s52, 31
	s_lshl_b64 s[54:55], s[52:53], 19
	s_add_u32 s76, s42, s54
	s_addc_u32 s77, s43, s55
	s_and_b64 s[54:55], s[6:7], exec
	s_cselect_b32 s53, s77, s83
	s_cselect_b32 s54, s76, s82
	s_ashr_i32 s51, s50, 31
	s_lshl_b64 s[56:57], s[50:51], 19
	s_add_u32 s78, s3, s56
	s_addc_u32 s79, s14, s57
	s_and_b64 s[56:57], s[6:7], exec
	s_cselect_b32 s51, s79, s85
	s_cselect_b32 s55, s78, s84
	s_add_u32 s82, s82, 0x40080
	s_addc_u32 s83, s83, 0
	s_add_u32 s56, s84, 0x100
	v_mov_b32_e32 v0, 0
	s_addc_u32 s57, s85, 0
	s_mov_b32 s58, -2
	.p2align 6

.LBB0_1147:
	s_ashr_i32 s49, s48, 31
	s_lshl_b64 s[50:51], s[48:49], 19
	s_add_u32 s50, s12, s50
	s_addc_u32 s51, s13, s51
	s_and_b64 s[52:53], s[4:5], exec
	s_cselect_b32 s49, s51, s79
	s_cselect_b32 s54, s50, s78
	s_ashr_i32 s47, s46, 31
	s_lshl_b64 s[52:53], s[46:47], 19
	s_add_u32 s52, s14, s52
	s_addc_u32 s53, s15, s53
	s_and_b64 s[58:59], s[4:5], exec
	s_cselect_b32 s47, s53, s81
	s_cselect_b32 s55, s52, s80
	s_add_u32 s78, s78, 0x40080
	s_addc_u32 s79, s79, 0
	s_add_u32 s58, s80, 0x100
	v_mov_b32_e32 v0, 0
	s_addc_u32 s59, s81, 0
	s_mov_b32 s66, -2
	s_waitcnt lgkmcnt(0)
	.p2align 6

.LBB0_1298:
	s_add_u32 s76, s76, 0xb0080
	s_addc_u32 s77, s77, 0
	s_add_u32 s55, s78, 0x100
	v_mov_b32_e32 v0, 0
	s_addc_u32 s58, s79, 0
	s_mov_b32 s59, -2
	.p2align 6

.LBB0_1759:
	s_ashr_i32 s49, s48, 31
	s_lshl_b64 s[50:51], s[48:49], 19
	s_add_u32 s50, s12, s50
	s_addc_u32 s51, s13, s51
	s_and_b64 s[52:53], s[4:5], exec
	s_cselect_b32 s49, s51, s79
	s_cselect_b32 s54, s50, s78
	s_ashr_i32 s47, s46, 31
	s_lshl_b64 s[52:53], s[46:47], 19
	s_add_u32 s52, s14, s52
	s_addc_u32 s53, s15, s53
	s_and_b64 s[66:67], s[4:5], exec
	s_cselect_b32 s47, s53, s81
	s_cselect_b32 s55, s52, s80
	s_add_u32 s78, s78, 0x40080
	s_addc_u32 s79, s79, 0
	s_add_u32 s66, s80, 0x100
	v_mov_b32_e32 v0, 0
	s_addc_u32 s67, s81, 0
	s_mov_b32 s68, -2
	s_waitcnt lgkmcnt(0)
	.p2align 6

.LBB0_2036:
	s_ashr_i32 s53, s52, 31
	s_lshl_b64 s[54:55], s[52:53], 19
	s_add_u32 s58, s42, s54
	s_addc_u32 s59, s43, s55
	s_and_b64 s[54:55], s[6:7], exec
	s_cselect_b32 s53, s59, s77
	s_cselect_b32 s54, s58, s76
	s_ashr_i32 s51, s50, 31
	s_lshl_b64 s[56:57], s[50:51], 19
	s_add_u32 s72, s3, s56
	s_addc_u32 s73, s14, s57
	s_and_b64 s[56:57], s[6:7], exec
	s_cselect_b32 s51, s73, s79
	s_cselect_b32 s55, s72, s78
	s_add_u32 s76, s76, 0x40080
	s_addc_u32 s77, s77, 0
	s_add_u32 s56, s78, 0x100
	v_mov_b32_e32 v0, 0
	s_addc_u32 s57, s79, 0
	s_mov_b32 s66, -2
	.p2align 6

.LBB0_2191:
	s_ashr_i32 s47, s46, 31
	s_lshl_b64 s[48:49], s[46:47], 19
	s_add_u32 s48, s12, s48
	s_addc_u32 s49, s13, s49
	s_and_b64 s[50:51], s[4:5], exec
	s_cselect_b32 s47, s49, s59
	s_cselect_b32 s53, s48, s58
	s_ashr_i32 s45, s44, 31
	s_lshl_b64 s[50:51], s[44:45], 19
	s_add_u32 s50, s14, s50
	s_addc_u32 s51, s15, s51
	s_and_b64 s[66:67], s[4:5], exec
	s_cselect_b32 s45, s51, s73
	s_cselect_b32 s66, s50, s72
	s_add_u32 s58, s58, 0x40080
	s_addc_u32 s59, s59, 0
	s_add_u32 s67, s72, 0x100
	v_mov_b32_e32 v0, 0
	s_addc_u32 s68, s73, 0
	s_mov_b32 s69, -2
	s_waitcnt lgkmcnt(0)
	.p2align 6

.LBB0_2340:
	s_add_u32 s16, s16, 0xb0080
	s_addc_u32 s17, s17, 0
	s_add_u32 s43, s18, 0x100
	v_mov_b32_e32 v0, 0
	s_addc_u32 s44, s19, 0
	s_mov_b32 s45, -2
	.p2align 6
